# sa2 + next-unit queue pop issued at unit start (latency covered by the unit's first load wait)
# baseline (speedup 1.0000x reference)
.LBB0_755:
	s_mov_b32 s98, 0
	v_writelane_b32 v252, s84, 6
	s_nop 1
	v_writelane_b32 v252, s85, 7
	s_or_b64 exec, exec, s[0:1]
	s_add_u32 s89, s66, 0x10000000
	s_addc_u32 s90, s67, 0
	s_add_u32 s91, s66, 0x14000000
	s_addc_u32 s92, s67, 0
	s_add_u32 s93, s66, 0x900000
	s_addc_u32 s94, s67, 0
	s_add_u32 s44, s66, 0x700000
	s_addc_u32 s45, s67, 0
	s_add_u32 s46, s66, 0x18000000
	s_addc_u32 s47, s67, 0
	s_add_u32 s50, s66, 0x1c000000
	s_addc_u32 s51, s67, 0
	s_add_u32 s60, s66, 0x23ff0020
	s_addc_u32 s61, s67, 0
	s_add_u32 s70, s66, 0x20000000
	s_addc_u32 s71, s67, 0
	s_add_i32 s95, 0, 0x22000
	s_add_i32 s0, 0, 0x14c00
	s_mov_b32 s80, 0xffff0000
	s_mov_b32 s73, 0
	s_waitcnt lgkmcnt(0)
	v_mov_b32_e32 v0, 0
	v_mov_b32_e32 v212, s95
	s_mov_b64 s[74:75], 0x10000
	s_mov_b64 s[76:77], 0x20000
	s_mov_b32 s96, 0xffff
	s_mov_b32 s42, 0x3f803f80
	s_mov_b64 s[78:79], 0x30000
	v_writelane_b32 v252, s0, 8
	s_mov_b32 s81, -1
	s_mov_b32 s88, 0x42b40000
	s_movk_i32 s48, 0x110
	s_add_i32 s0, 0, 0x22400
	v_mov_b32_e32 v213, 0x358637bd
	v_mov_b32_e32 v214, 0x260
	s_mov_b32 s52, 0xda24260
	v_mov_b32_e32 v215, 0x3f803f80
	v_mov_b32_e32 v216, 0xff800000
	v_mbcnt_hi_u32_b32 v211, -1, v208
	v_mov_b32_e32 v217, 0x440
	v_mov_b32_e32 v218, 0x1100
	v_mov_b32_e32 v219, 0x1540
	v_mov_b32_e32 v220, 0x2200
	v_mov_b32_e32 v221, 0x2640
	v_mov_b32_e32 v222, 0x3300
	v_mov_b32_e32 v223, 0x3740
	v_mov_b32_e32 v224, 0x7149f2ca
	s_barrier
	v_writelane_b32 v252, s0, 9
	s_branch .LBB0_759

.LBB0_759:
	s_and_saveexec_b64 s[0:1], s[38:39]
	s_cbranch_execz .LBB0_763
	s_mov_b64 s[6:7], exec
	v_mbcnt_lo_u32_b32 v1, s6, 0
	v_mbcnt_hi_u32_b32 v1, s7, v1
	v_cmp_eq_u32_e32 vcc, 0, v1
	s_and_saveexec_b64 s[4:5], vcc
	s_cbranch_execz .LBB0_762
	s_cmp_lg_u32 s98, 0
	s_cbranch_scc1 .Lpop_have
	s_bcnt1_i32_b64 s6, s[6:7]
	v_mov_b32_e32 v253, s6
	global_atomic_add v253, v0, v253, s[66:67] sc0
.Lpop_have:
.LBB0_762:
	s_or_b64 exec, exec, s[4:5]
	s_waitcnt vmcnt(0)
	v_readfirstlane_b32 s4, v253
	v_mov_b32_e32 v2, s95
	s_nop 0
	v_add_u32_e32 v1, s4, v1
	ds_write_b32 v2, v1
.LBB0_763:
	s_or_b64 exec, exec, s[0:1]
	s_waitcnt lgkmcnt(0)
	s_barrier
	ds_read_b32 v1, v212
	s_movk_i32 s0, 0x87f
	s_waitcnt lgkmcnt(0)
	s_barrier
	v_cmp_lt_i32_e32 vcc, s0, v1
	v_readfirstlane_b32 s53, v1
	s_mov_b64 s[0:1], -1
	s_cbranch_vccnz .LBB0_758
	s_and_saveexec_b64 s[100:101], s[38:39]
	s_cbranch_execz .Lpop_pf_skip
	v_mov_b32_e32 v253, 1
	global_atomic_add v253, v0, v253, s[66:67] sc0
.Lpop_pf_skip:
	s_mov_b64 exec, s[100:101]
	s_mov_b32 s98, 1
	s_cmpk_gt_i32 s53, 0x7f
	s_cbranch_scc0 .LBB0_803
	s_add_i32 s0, s53, 0xffffff80
	s_and_b32 s6, s0, 0xff
	s_lshl_b32 s1, s6, 13
	s_add_u32 s4, s93, s1
	s_addc_u32 s5, s94, 0
	v_mov_b32_e32 v225, v210
	s_and_b32 s10, s0, 0xffffff00
	s_sub_i32 s19, 0x800, s10
	v_lshlrev_b32_e32 v2, 2, v225
	v_readfirstlane_b32 s9, v225
	v_cmp_gt_i32_e32 vcc, s19, v2
	v_mov_b32_e32 v18, 0
	v_mov_b32_e32 v19, 0
	v_mov_b32_e32 v20, 0
	v_mov_b32_e32 v21, 0
	s_and_saveexec_b64 s[0:1], vcc
	s_cbranch_execz .LBB0_767
	v_ashrrev_i32_e32 v3, 31, v2
	v_lshl_add_u64 v[2:3], v[2:3], 2, s[4:5]
	global_load_dwordx4 v[18:21], v[2:3], off

	.amdhsa_kernel _Z8fwd_mega4Args
		.amdhsa_group_segment_fixed_size 0
		.amdhsa_private_segment_fixed_size 0
		.amdhsa_kernarg_size 432
		.amdhsa_user_sgpr_count 2
		.amdhsa_user_sgpr_dispatch_ptr 0
		.amdhsa_user_sgpr_queue_ptr 0
		.amdhsa_user_sgpr_kernarg_segment_ptr 1
		.amdhsa_user_sgpr_dispatch_id 0
		.amdhsa_user_sgpr_kernarg_preload_length 0
		.amdhsa_user_sgpr_kernarg_preload_offset 0
		.amdhsa_user_sgpr_private_segment_size 0
		.amdhsa_uses_dynamic_stack 0
		.amdhsa_enable_private_segment 0
		.amdhsa_system_sgpr_workgroup_id_x 1
		.amdhsa_system_sgpr_workgroup_id_y 0
		.amdhsa_system_sgpr_workgroup_id_z 0
		.amdhsa_system_sgpr_workgroup_info 0
		.amdhsa_system_vgpr_workitem_id 2
		.amdhsa_next_free_vgpr 254
		.amdhsa_next_free_sgpr 102
		.amdhsa_accum_offset 256
		.amdhsa_reserve_vcc 1
		.amdhsa_float_round_mode_32 0
		.amdhsa_float_round_mode_16_64 0
		.amdhsa_float_denorm_mode_32 3
		.amdhsa_float_denorm_mode_16_64 3
		.amdhsa_dx10_clamp 1
		.amdhsa_ieee_mode 1
		.amdhsa_fp16_overflow 0
		.amdhsa_tg_split 0
		.amdhsa_exception_fp_ieee_invalid_op 0
		.amdhsa_exception_fp_denorm_src 0
		.amdhsa_exception_fp_ieee_div_zero 0
		.amdhsa_exception_fp_ieee_overflow 0
		.amdhsa_exception_fp_ieee_underflow 0
		.amdhsa_exception_fp_ieee_inexact 0
		.amdhsa_exception_int_div_zero 0
	.end_amdhsa_kernel

.Lfunc_end0:
	.size	_Z8fwd_mega4Args, .Lfunc_end0-_Z8fwd_mega4Args
	.set _Z8fwd_mega4Args.num_vgpr, 254
	.set _Z8fwd_mega4Args.num_agpr, 0
	.set _Z8fwd_mega4Args.numbered_sgpr, 102
	.set _Z8fwd_mega4Args.num_named_barrier, 0
	.set _Z8fwd_mega4Args.private_seg_size, 0
	.set _Z8fwd_mega4Args.uses_vcc, 1
	.set _Z8fwd_mega4Args.uses_flat_scratch, 0
	.set _Z8fwd_mega4Args.has_dyn_sized_stack, 0
	.set _Z8fwd_mega4Args.has_recursion, 0
	.set _Z8fwd_mega4Args.has_indirect_call, 0

amdhsa.kernels:
  - .agpr_count:     0
    .args:
      - .offset:         0
        .size:           176
        .value_kind:     by_value
      - .offset:         176
        .size:           4
        .value_kind:     hidden_block_count_x
      - .offset:         180
        .size:           4
        .value_kind:     hidden_block_count_y
      - .offset:         184
        .size:           4
        .value_kind:     hidden_block_count_z
      - .offset:         188
        .size:           2
        .value_kind:     hidden_group_size_x
      - .offset:         190
        .size:           2
        .value_kind:     hidden_group_size_y
      - .offset:         192
        .size:           2
        .value_kind:     hidden_group_size_z
      - .offset:         194
        .size:           2
        .value_kind:     hidden_remainder_x
      - .offset:         196
        .size:           2
        .value_kind:     hidden_remainder_y
      - .offset:         198
        .size:           2
        .value_kind:     hidden_remainder_z
      - .offset:         216
        .size:           8
        .value_kind:     hidden_global_offset_x
      - .offset:         224
        .size:           8
        .value_kind:     hidden_global_offset_y
      - .offset:         232
        .size:           8
        .value_kind:     hidden_global_offset_z
      - .offset:         240
        .size:           2
        .value_kind:     hidden_grid_dims
      - .offset:         264
        .size:           8
        .value_kind:     hidden_multigrid_sync_arg
      - .offset:         296
        .size:           4
        .value_kind:     hidden_dynamic_lds_size
    .group_segment_fixed_size: 0
    .kernarg_segment_align: 8
    .kernarg_segment_size: 432
    .language:       OpenCL C
    .language_version:
      - 2
      - 0
    .max_flat_workgroup_size: 512
    .name:           _Z8fwd_mega4Args
    .private_segment_fixed_size: 0
    .sgpr_count:     108
    .sgpr_spill_count: 10
    .symbol:         _Z8fwd_mega4Args.kd
    .uniform_work_group_size: 1
    .uses_dynamic_stack: false
    .vgpr_count:     254
    .vgpr_spill_count: 0
    .wavefront_size: 64
